# v42 + stick-breaking attn: 8 K-fragment LDS reads issued up front with counted lgkmcnt waits
# baseline (speedup 1.0000x reference)
.LBB0_96:
	v_cmp_le_i32_e32 vcc, s0, v103
	s_and_saveexec_b64 s[20:21], vcc
	s_cbranch_execz .LBB0_89
	v_add_u32_e32 v166, v105, v104
	v_add_u32_e32 v170, v105, v106
	v_add_u32_e32 v174, v105, v107
	v_add_u32_e32 v178, v105, v108
	v_add_u32_e32 v182, v109, v104
	v_add_u32_e32 v186, v109, v106
	v_add_u32_e32 v190, v109, v107
	v_add_u32_e32 v194, v109, v108
	ds_read_b128 v[166:169], v166
	ds_read_b128 v[170:173], v170
	ds_read_b128 v[174:177], v174
	ds_read_b128 v[178:181], v178
	ds_read_b128 v[182:185], v182
	ds_read_b128 v[186:189], v186
	ds_read_b128 v[190:193], v190
	ds_read_b128 v[194:197], v194
	s_or_b32 s7, s0, 63
	v_cmp_lt_i32_e32 vcc, s7, v102
	s_waitcnt lgkmcnt(7)
	v_mfma_f32_32x32x16_bf16 v[50:65], v[166:169], v[66:69], 0
	s_waitcnt lgkmcnt(6)
	v_mfma_f32_32x32x16_bf16 v[50:65], v[170:173], v[70:73], v[50:65]
	s_waitcnt lgkmcnt(5)
	v_mfma_f32_32x32x16_bf16 v[50:65], v[174:177], v[74:77], v[50:65]
	s_waitcnt lgkmcnt(4)
	v_mfma_f32_32x32x16_bf16 v[50:65], v[178:181], v[78:81], v[50:65]
	s_waitcnt lgkmcnt(3)
	v_mfma_f32_32x32x16_bf16 v[34:49], v[182:185], v[66:69], 0
	s_waitcnt lgkmcnt(2)
	v_mfma_f32_32x32x16_bf16 v[34:49], v[186:189], v[70:73], v[34:49]
	s_waitcnt lgkmcnt(1)
	v_mfma_f32_32x32x16_bf16 v[34:49], v[190:193], v[74:77], v[34:49]
	s_waitcnt lgkmcnt(0)
	v_mfma_f32_32x32x16_bf16 v[34:49], v[194:197], v[78:81], v[34:49]
	s_nop 4
	v_mul_f32_e32 v0, 0x3fb8aa3b, v50
	v_exp_f32_e64 v127, -|v0|
	v_min_f32_e32 v0, 0, v0
	v_add_f32_e32 v127, 1.0, v127
	v_mul_f32_e32 v128, 0x3fb8aa3b, v51
	v_exp_f32_e64 v130, -|v128|
	v_min_f32_e32 v128, 0, v128
	v_log_f32_e32 v127, v127
	v_or_b32_e32 v129, s0, v99
	v_add_f32_e32 v130, 1.0, v130
	v_log_f32_e32 v130, v130
	v_cmp_lt_i32_e64 s[42:43], v129, v98
	v_sub_f32_e32 v127, v0, v127
	s_or_b64 s[42:43], vcc, s[42:43]
	v_sub_f32_e32 v128, v128, v130
	v_mul_f32_e32 v130, 0x3fb8aa3b, v52
	v_exp_f32_e64 v131, -|v130|
	v_cndmask_b32_e64 v0, v245, v127, s[42:43]
	v_fmac_f32_e32 v127, 0xbfb8aa3b, v50
	v_add_f32_e32 v50, 0, v127
	v_add_f32_e32 v131, 1.0, v131
	v_log_f32_e32 v131, v131
	v_cndmask_b32_e64 v127, 0, v50, s[42:43]
	v_or_b32_e32 v50, 1, v129
	v_cmp_lt_i32_e64 s[42:43], v50, v98
	v_min_f32_e32 v130, 0, v130
	s_or_b64 s[42:43], vcc, s[42:43]
	v_sub_f32_e32 v130, v130, v131
	v_mul_f32_e32 v131, 0x3fb8aa3b, v53
	v_cndmask_b32_e64 v50, v245, v128, s[42:43]
	v_fmac_f32_e32 v128, 0xbfb8aa3b, v51
	v_exp_f32_e64 v132, -|v131|
	v_cndmask_b32_e64 v51, 0, v128, s[42:43]
	v_add_f32_e32 v128, v51, v127
	v_or_b32_e32 v127, 2, v129
	v_cmp_lt_i32_e64 s[42:43], v127, v98
	s_or_b64 s[42:43], vcc, s[42:43]
	v_add_f32_e32 v132, 1.0, v132
	v_cndmask_b32_e64 v127, v245, v130, s[42:43]
	v_fmac_f32_e32 v130, 0xbfb8aa3b, v52
	v_log_f32_e32 v132, v132
	v_cndmask_b32_e64 v52, 0, v130, s[42:43]
	v_add_f32_e32 v130, v52, v128
	v_or_b32_e32 v128, 3, v129
	v_min_f32_e32 v131, 0, v131
	v_cmp_lt_i32_e64 s[42:43], v128, v98
	v_sub_f32_e32 v131, v131, v132
	s_or_b64 s[42:43], vcc, s[42:43]
	v_cndmask_b32_e64 v128, v245, v131, s[42:43]
	v_fmac_f32_e32 v131, 0xbfb8aa3b, v53
	v_cndmask_b32_e64 v53, 0, v131, s[42:43]
	v_mul_f32_e32 v131, 0x3fb8aa3b, v54
	v_exp_f32_e64 v132, -|v131|
	v_min_f32_e32 v131, 0, v131
	v_add_f32_e32 v133, v53, v130
	v_or_b32_e32 v130, 8, v129
	v_add_f32_e32 v132, 1.0, v132
	v_log_f32_e32 v132, v132
	v_cmp_lt_i32_e64 s[42:43], v130, v98
	s_or_b64 s[42:43], vcc, s[42:43]
	s_mov_b32 s0, 0xc3200000
	v_sub_f32_e32 v131, v131, v132
	v_mul_f32_e32 v132, 0x3fb8aa3b, v55
	v_exp_f32_e64 v134, -|v132|
	v_min_f32_e32 v132, 0, v132
	v_cndmask_b32_e64 v130, v245, v131, s[42:43]
	v_fmac_f32_e32 v131, 0xbfb8aa3b, v54
	v_add_f32_e32 v134, 1.0, v134
	v_log_f32_e32 v134, v134
	v_add_f32_e32 v54, 0, v131
	v_cndmask_b32_e64 v131, 0, v54, s[42:43]
	v_or_b32_e32 v54, 9, v129
	v_sub_f32_e32 v132, v132, v134
	v_mul_f32_e32 v134, 0x3fb8aa3b, v56
	v_exp_f32_e64 v135, -|v134|
	v_cmp_lt_i32_e64 s[42:43], v54, v98
	v_min_f32_e32 v134, 0, v134
	s_or_b64 s[42:43], vcc, s[42:43]
	v_add_f32_e32 v135, 1.0, v135
	v_log_f32_e32 v135, v135
	v_cndmask_b32_e64 v54, v245, v132, s[42:43]
	v_fmac_f32_e32 v132, 0xbfb8aa3b, v55
	v_cndmask_b32_e64 v55, 0, v132, s[42:43]
	v_sub_f32_e32 v134, v134, v135
	v_mul_f32_e32 v135, 0x3fb8aa3b, v57
	v_exp_f32_e64 v136, -|v135|
	v_add_f32_e32 v132, v55, v131
	v_or_b32_e32 v131, 10, v129
	v_cmp_lt_i32_e64 s[42:43], v131, v98
	s_or_b64 s[42:43], vcc, s[42:43]
	v_add_f32_e32 v136, 1.0, v136
	v_cndmask_b32_e64 v131, v245, v134, s[42:43]
	v_fmac_f32_e32 v134, 0xbfb8aa3b, v56
	v_log_f32_e32 v136, v136
	v_cndmask_b32_e64 v56, 0, v134, s[42:43]
	v_add_f32_e32 v134, v56, v132
	v_or_b32_e32 v132, 11, v129
	v_min_f32_e32 v135, 0, v135
	v_cmp_lt_i32_e64 s[42:43], v132, v98
	v_sub_f32_e32 v135, v135, v136
	s_or_b64 s[42:43], vcc, s[42:43]
	v_cndmask_b32_e64 v132, v245, v135, s[42:43]
	v_fmac_f32_e32 v135, 0xbfb8aa3b, v57
	v_cndmask_b32_e64 v57, 0, v135, s[42:43]
	v_mul_f32_e32 v135, 0x3fb8aa3b, v58
	v_exp_f32_e64 v137, -|v135|
	v_min_f32_e32 v135, 0, v135
	v_add_f32_e32 v136, v57, v134
	v_or_b32_e32 v134, 16, v129
	v_add_f32_e32 v137, 1.0, v137
	v_log_f32_e32 v137, v137
	v_cmp_lt_i32_e64 s[42:43], v134, v98
	s_or_b64 s[42:43], vcc, s[42:43]
	v_sub_f32_e32 v135, v135, v137
	v_mul_f32_e32 v137, 0x3fb8aa3b, v59
	v_exp_f32_e64 v138, -|v137|
	v_min_f32_e32 v137, 0, v137
	v_cndmask_b32_e64 v134, v245, v135, s[42:43]
	v_fmac_f32_e32 v135, 0xbfb8aa3b, v58
	v_add_f32_e32 v138, 1.0, v138
	v_log_f32_e32 v138, v138
	v_add_f32_e32 v58, 0, v135
	v_cndmask_b32_e64 v135, 0, v58, s[42:43]
	v_or_b32_e32 v58, 17, v129
	v_sub_f32_e32 v137, v137, v138
	v_mul_f32_e32 v138, 0x3fb8aa3b, v60
	v_exp_f32_e64 v139, -|v138|
	v_min_f32_e32 v138, 0, v138
	v_cmp_lt_i32_e64 s[42:43], v58, v98
	s_or_b64 s[42:43], vcc, s[42:43]
	v_add_f32_e32 v139, 1.0, v139
	v_log_f32_e32 v139, v139
	v_cndmask_b32_e64 v58, v245, v137, s[42:43]
	v_fmac_f32_e32 v137, 0xbfb8aa3b, v59
	v_cndmask_b32_e64 v59, 0, v137, s[42:43]
	v_sub_f32_e32 v138, v138, v139
	v_mul_f32_e32 v139, 0x3fb8aa3b, v61
	v_exp_f32_e64 v140, -|v139|
	v_min_f32_e32 v139, 0, v139
	v_add_f32_e32 v137, v59, v135
	v_or_b32_e32 v135, 18, v129
	v_add_f32_e32 v140, 1.0, v140
	v_log_f32_e32 v140, v140
	v_cmp_lt_i32_e64 s[42:43], v135, v98
	s_or_b64 s[42:43], vcc, s[42:43]
	v_sub_f32_e32 v139, v139, v140
	v_mul_f32_e32 v140, 0x3fb8aa3b, v62
	v_exp_f32_e64 v141, -|v140|
	v_min_f32_e32 v140, 0, v140
	v_cndmask_b32_e64 v135, v245, v138, s[42:43]
	v_fmac_f32_e32 v138, 0xbfb8aa3b, v60
	v_add_f32_e32 v141, 1.0, v141
	v_log_f32_e32 v141, v141
	v_cndmask_b32_e64 v60, 0, v138, s[42:43]
	v_add_f32_e32 v138, v60, v137
	v_or_b32_e32 v137, 19, v129
	v_sub_f32_e32 v140, v140, v141
	v_mul_f32_e32 v141, 0x3fb8aa3b, v63
	v_exp_f32_e64 v142, -|v141|
	v_min_f32_e32 v141, 0, v141
	v_cmp_lt_i32_e64 s[42:43], v137, v98
	s_or_b64 s[42:43], vcc, s[42:43]
	v_add_f32_e32 v142, 1.0, v142
	v_log_f32_e32 v142, v142
	v_cndmask_b32_e64 v137, v245, v139, s[42:43]
	v_fmac_f32_e32 v139, 0xbfb8aa3b, v61
	v_cndmask_b32_e64 v61, 0, v139, s[42:43]
	v_sub_f32_e32 v141, v141, v142
	v_mul_f32_e32 v142, 0x3fb8aa3b, v64
	v_exp_f32_e64 v143, -|v142|
	v_min_f32_e32 v142, 0, v142
	v_add_f32_e32 v139, v61, v138
	v_or_b32_e32 v138, 24, v129
	v_add_f32_e32 v143, 1.0, v143
	v_log_f32_e32 v143, v143
	v_cmp_lt_i32_e64 s[42:43], v138, v98
	s_or_b64 s[42:43], vcc, s[42:43]
	v_sub_f32_e32 v142, v142, v143
	v_mul_f32_e32 v143, 0x3fb8aa3b, v65
	v_exp_f32_e64 v144, -|v143|
	v_min_f32_e32 v143, 0, v143
	v_cndmask_b32_e64 v138, v245, v140, s[42:43]
	v_fmac_f32_e32 v140, 0xbfb8aa3b, v62
	v_add_f32_e32 v144, 1.0, v144
	v_log_f32_e32 v144, v144
	v_add_f32_e32 v62, 0, v140
	v_cndmask_b32_e64 v140, 0, v62, s[42:43]
	v_or_b32_e32 v62, 25, v129
	v_sub_f32_e32 v143, v143, v144
	v_mul_f32_e32 v144, 0x3fb8aa3b, v34
	v_exp_f32_e64 v145, -|v144|
	v_min_f32_e32 v144, 0, v144
	v_cmp_lt_i32_e64 s[42:43], v62, v98
	s_or_b64 s[42:43], vcc, s[42:43]
	v_add_f32_e32 v145, 1.0, v145
	v_log_f32_e32 v145, v145
	v_cndmask_b32_e64 v62, v245, v141, s[42:43]
	v_fmac_f32_e32 v141, 0xbfb8aa3b, v63
	v_cndmask_b32_e64 v63, 0, v141, s[42:43]
	v_sub_f32_e32 v144, v144, v145
	v_mul_f32_e32 v145, 0x3fb8aa3b, v35
	v_exp_f32_e64 v146, -|v145|
	v_min_f32_e32 v145, 0, v145
	v_add_f32_e32 v141, v63, v140
	v_or_b32_e32 v140, 26, v129
	v_add_f32_e32 v146, 1.0, v146
	v_log_f32_e32 v146, v146
	v_cmp_lt_i32_e64 s[42:43], v140, v98
	s_or_b64 s[42:43], vcc, s[42:43]
	v_sub_f32_e32 v145, v145, v146
	v_mul_f32_e32 v146, 0x3fb8aa3b, v36
	v_exp_f32_e64 v147, -|v146|
	v_min_f32_e32 v146, 0, v146
	v_cndmask_b32_e64 v140, v245, v142, s[42:43]
	v_fmac_f32_e32 v142, 0xbfb8aa3b, v64
	v_add_f32_e32 v147, 1.0, v147
	v_log_f32_e32 v147, v147
	v_cndmask_b32_e64 v64, 0, v142, s[42:43]
	v_add_f32_e32 v142, v64, v141
	v_or_b32_e32 v141, 27, v129
	v_sub_f32_e32 v146, v146, v147
	v_mul_f32_e32 v147, 0x3fb8aa3b, v37
	v_exp_f32_e64 v148, -|v147|
	v_cmp_lt_i32_e64 s[42:43], v141, v98
	s_or_b64 s[42:43], vcc, s[42:43]
	v_min_f32_e32 v147, 0, v147
	v_add_f32_e32 v148, 1.0, v148
	v_cndmask_b32_e64 v141, v245, v143, s[42:43]
	v_fmac_f32_e32 v143, 0xbfb8aa3b, v65
	v_log_f32_e32 v148, v148
	v_cndmask_b32_e64 v65, 0, v143, s[42:43]
	v_add_f32_e32 v143, v65, v142
	v_or_b32_e32 v142, 32, v129
	v_cmp_lt_i32_e64 s[42:43], v142, v98
	s_or_b64 s[42:43], vcc, s[42:43]
	v_sub_f32_e32 v147, v147, v148
	v_mul_f32_e32 v148, 0x3fb8aa3b, v38
	v_cndmask_b32_e64 v142, v245, v144, s[42:43]
	v_fmac_f32_e32 v144, 0xbfb8aa3b, v34
	v_exp_f32_e64 v149, -|v148|
	v_add_f32_e32 v34, 0, v144
	v_cndmask_b32_e64 v144, 0, v34, s[42:43]
	v_or_b32_e32 v34, 33, v129
	v_cmp_lt_i32_e64 s[42:43], v34, v98
	s_or_b64 s[42:43], vcc, s[42:43]
	v_add_f32_e32 v149, 1.0, v149
	v_cndmask_b32_e64 v34, v245, v145, s[42:43]
	v_fmac_f32_e32 v145, 0xbfb8aa3b, v35
	v_log_f32_e32 v149, v149
	v_cndmask_b32_e64 v35, 0, v145, s[42:43]
	v_add_f32_e32 v145, v35, v144
	v_or_b32_e32 v144, 34, v129
	v_cmp_lt_i32_e64 s[42:43], v144, v98
	v_min_f32_e32 v148, 0, v148
	s_or_b64 s[42:43], vcc, s[42:43]
	v_sub_f32_e32 v148, v148, v149
	v_mul_f32_e32 v149, 0x3fb8aa3b, v39
	v_cndmask_b32_e64 v144, v245, v146, s[42:43]
	v_fmac_f32_e32 v146, 0xbfb8aa3b, v36
	v_exp_f32_e64 v150, -|v149|
	v_cndmask_b32_e64 v36, 0, v146, s[42:43]
	v_add_f32_e32 v146, v36, v145
	v_or_b32_e32 v145, 35, v129
	v_cmp_lt_i32_e64 s[42:43], v145, v98
	s_or_b64 s[42:43], vcc, s[42:43]
	v_add_f32_e32 v150, 1.0, v150
	v_cndmask_b32_e64 v145, v245, v147, s[42:43]
	v_fmac_f32_e32 v147, 0xbfb8aa3b, v37
	v_log_f32_e32 v150, v150
	v_cndmask_b32_e64 v37, 0, v147, s[42:43]
	v_add_f32_e32 v147, v37, v146
	v_or_b32_e32 v146, 40, v129
	v_cmp_lt_i32_e64 s[42:43], v146, v98
	v_min_f32_e32 v149, 0, v149
	s_or_b64 s[42:43], vcc, s[42:43]
	v_sub_f32_e32 v149, v149, v150
	v_mul_f32_e32 v150, 0x3fb8aa3b, v40
	v_cndmask_b32_e64 v146, v245, v148, s[42:43]
	v_fmac_f32_e32 v148, 0xbfb8aa3b, v38
	v_exp_f32_e64 v151, -|v150|
	v_add_f32_e32 v38, 0, v148
	v_cndmask_b32_e64 v148, 0, v38, s[42:43]
	v_or_b32_e32 v38, 41, v129
	v_cmp_lt_i32_e64 s[42:43], v38, v98
	s_or_b64 s[42:43], vcc, s[42:43]
	v_add_f32_e32 v151, 1.0, v151
	v_cndmask_b32_e64 v38, v245, v149, s[42:43]
	v_fmac_f32_e32 v149, 0xbfb8aa3b, v39
	v_log_f32_e32 v151, v151
	v_cndmask_b32_e64 v39, 0, v149, s[42:43]
	v_add_f32_e32 v149, v39, v148
	v_or_b32_e32 v148, 42, v129
	v_min_f32_e32 v150, 0, v150
	v_cmp_lt_i32_e64 s[42:43], v148, v98
	v_sub_f32_e32 v150, v150, v151
	s_or_b64 s[42:43], vcc, s[42:43]
	v_cndmask_b32_e64 v148, v245, v150, s[42:43]
	v_fmac_f32_e32 v150, 0xbfb8aa3b, v40
	v_cndmask_b32_e64 v40, 0, v150, s[42:43]
	v_mul_f32_e32 v150, 0x3fb8aa3b, v41
	v_exp_f32_e64 v152, -|v150|
	v_min_f32_e32 v150, 0, v150
	v_add_f32_e32 v151, v40, v149
	v_or_b32_e32 v149, 43, v129
	v_add_f32_e32 v152, 1.0, v152
	v_log_f32_e32 v152, v152
	v_cmp_lt_i32_e64 s[42:43], v149, v98
	s_or_b64 s[42:43], vcc, s[42:43]
	v_sub_f32_e32 v150, v150, v152
	v_mul_f32_e32 v152, 0x3fb8aa3b, v42
	v_exp_f32_e64 v153, -|v152|
	v_cndmask_b32_e64 v149, v245, v150, s[42:43]
	v_fmac_f32_e32 v150, 0xbfb8aa3b, v41
	v_or_b32_e32 v41, 48, v129
	v_add_f32_e32 v153, 1.0, v153
	v_log_f32_e32 v153, v153
	v_cndmask_b32_e64 v150, 0, v150, s[42:43]
	v_min_f32_e32 v152, 0, v152
	v_cmp_lt_i32_e64 s[42:43], v41, v98
	v_sub_f32_e32 v152, v152, v153
	s_or_b64 s[42:43], vcc, s[42:43]
	v_cndmask_b32_e64 v153, v245, v152, s[42:43]
	v_fmac_f32_e32 v152, 0xbfb8aa3b, v42
	v_add_f32_e32 v41, 0, v152
	v_mul_f32_e32 v152, 0x3fb8aa3b, v43
	v_exp_f32_e64 v154, -|v152|
	v_min_f32_e32 v152, 0, v152
	v_or_b32_e32 v42, 49, v129
	v_cndmask_b32_e64 v41, 0, v41, s[42:43]
	v_add_f32_e32 v154, 1.0, v154
	v_log_f32_e32 v154, v154
	v_cmp_lt_i32_e64 s[42:43], v42, v98
	s_or_b64 s[42:43], vcc, s[42:43]
	v_add_f32_e32 v151, v150, v151
	v_sub_f32_e32 v152, v152, v154
	v_mul_f32_e32 v154, 0x3fb8aa3b, v44
	v_exp_f32_e64 v155, -|v154|
	v_min_f32_e32 v154, 0, v154
	v_cndmask_b32_e64 v42, v245, v152, s[42:43]
	v_fmac_f32_e32 v152, 0xbfb8aa3b, v43
	v_add_f32_e32 v155, 1.0, v155
	v_log_f32_e32 v155, v155
	v_cndmask_b32_e64 v43, 0, v152, s[42:43]
	v_or_b32_e32 v152, 50, v129
	v_cmp_lt_i32_e64 s[42:43], v152, v98
	v_sub_f32_e32 v154, v154, v155
	v_mul_f32_e32 v155, 0x3fb8aa3b, v45
	v_exp_f32_e64 v156, -|v155|
	v_min_f32_e32 v155, 0, v155
	s_or_b64 s[42:43], vcc, s[42:43]
	v_cndmask_b32_e64 v152, v245, v154, s[42:43]
	v_add_f32_e32 v156, 1.0, v156
	v_log_f32_e32 v156, v156
	v_fmac_f32_e32 v154, 0xbfb8aa3b, v44
	v_cndmask_b32_e64 v44, 0, v154, s[42:43]
	v_or_b32_e32 v154, 51, v129
	v_sub_f32_e32 v155, v155, v156
	v_mul_f32_e32 v156, 0x3fb8aa3b, v46
	v_exp_f32_e64 v157, -|v156|
	v_cmp_lt_i32_e64 s[42:43], v154, v98
	s_or_b64 s[42:43], vcc, s[42:43]
	v_add_f32_e32 v41, v43, v41
	v_add_f32_e32 v157, 1.0, v157
	v_cndmask_b32_e64 v154, v245, v155, s[42:43]
	v_fmac_f32_e32 v155, 0xbfb8aa3b, v45
	v_log_f32_e32 v157, v157
	v_add_f32_e32 v41, v44, v41
	v_cndmask_b32_e64 v45, 0, v155, s[42:43]
	v_add_f32_e32 v155, v45, v41
	v_or_b32_e32 v41, 56, v129
	v_min_f32_e32 v156, 0, v156
	v_cmp_lt_i32_e64 s[42:43], v41, v98
	v_sub_f32_e32 v156, v156, v157
	s_or_b64 s[42:43], vcc, s[42:43]
	v_cndmask_b32_e64 v157, v245, v156, s[42:43]
	v_fmac_f32_e32 v156, 0xbfb8aa3b, v46
	v_add_f32_e32 v41, 0, v156
	v_mul_f32_e32 v156, 0x3fb8aa3b, v47
	v_exp_f32_e64 v158, -|v156|
	v_min_f32_e32 v156, 0, v156
	v_or_b32_e32 v46, 57, v129
	v_cndmask_b32_e64 v41, 0, v41, s[42:43]
	v_add_f32_e32 v158, 1.0, v158
	v_log_f32_e32 v158, v158
	v_cmp_lt_i32_e64 s[42:43], v46, v98
	s_or_b64 s[42:43], vcc, s[42:43]
	v_sub_f32_e32 v156, v156, v158
	v_mul_f32_e32 v158, 0x3fb8aa3b, v48
	v_exp_f32_e64 v159, -|v158|
	v_cndmask_b32_e64 v46, v245, v156, s[42:43]
	v_fmac_f32_e32 v156, 0xbfb8aa3b, v47
	v_cndmask_b32_e64 v47, 0, v156, s[42:43]
	v_add_f32_e32 v159, 1.0, v159
	v_log_f32_e32 v159, v159
	v_or_b32_e32 v156, 58, v129
	v_min_f32_e32 v158, 0, v158
	v_cmp_lt_i32_e64 s[42:43], v156, v98
	v_sub_f32_e32 v158, v158, v159
	s_or_b64 s[42:43], vcc, s[42:43]
	v_cndmask_b32_e64 v156, v245, v158, s[42:43]
	v_fmac_f32_e32 v158, 0xbfb8aa3b, v48
	v_cndmask_b32_e64 v48, 0, v158, s[42:43]
	v_mul_f32_e32 v158, 0x3fb8aa3b, v49
	v_exp_f32_e64 v159, -|v158|
	v_or_b32_e32 v129, 59, v129
	v_min_f32_e32 v158, 0, v158
	v_cmp_lt_i32_e64 s[42:43], v129, v98
	v_add_f32_e32 v159, 1.0, v159
	v_log_f32_e32 v159, v159
	s_or_b64 vcc, vcc, s[42:43]
	v_add_f32_e32 v41, v47, v41
	v_add_f32_e32 v41, v48, v41
	v_sub_f32_e32 v158, v158, v159
	v_cndmask_b32_e32 v129, v245, v158, vcc
	v_fmac_f32_e32 v158, 0xbfb8aa3b, v49
	v_cndmask_b32_e32 v49, 0, v158, vcc
	v_cmp_lt_i32_e32 vcc, v246, v252
	v_add_f32_e32 v158, v49, v41
	s_nop 0
	v_cndmask_b32_e32 v41, v242, v246, vcc
	v_lshlrev_b32_e32 v159, 2, v41
	ds_bpermute_b32 v160, v159, v133
	ds_bpermute_b32 v161, v159, v139
	ds_bpermute_b32 v162, v159, v143
	ds_bpermute_b32 v163, v159, v147
	ds_bpermute_b32 v164, v159, v151
	s_waitcnt lgkmcnt(4)
	v_add_f32_e32 v41, v133, v160
	ds_bpermute_b32 v133, v159, v136
	ds_bpermute_b32 v165, v159, v155
	ds_bpermute_b32 v159, v159, v158
	s_waitcnt lgkmcnt(3)
	v_add_f32_e32 v151, v151, v164
	v_add_f32_e32 v147, v147, v163
	v_add_f32_e32 v143, v143, v162
	s_waitcnt lgkmcnt(1)
	v_add_f32_e32 v155, v155, v165
	s_waitcnt lgkmcnt(0)
	v_add_f32_e32 v158, v158, v159
	v_cndmask_b32_e64 v159, 0, v159, s[40:41]
	v_add_f32_e32 v159, v126, v159
	v_add_f32_e32 v49, v49, v159
	v_add_f32_e32 v48, v48, v49
	v_add_f32_e32 v46, v46, v48
	v_add_f32_e32 v129, v129, v159
	v_exp_f32_e32 v159, v46
	v_add_f32_e32 v46, v47, v48
	v_add_f32_e32 v46, v157, v46
	v_exp_f32_e32 v157, v46
	v_add_f32_e32 v46, v126, v158
	v_cndmask_b32_e64 v47, 0, v165, s[40:41]
	v_add_f32_e32 v47, v47, v46
	v_add_f32_e32 v45, v45, v47
	v_add_f32_e32 v44, v44, v45
	v_add_f32_e32 v42, v42, v44
	v_add_f32_e32 v48, v154, v47
	v_exp_f32_e32 v154, v42
	v_add_f32_e32 v42, v43, v44
	v_add_f32_e32 v42, v153, v42
	v_exp_f32_e32 v153, v42
	v_add_f32_e32 v42, v155, v46
	v_cndmask_b32_e64 v43, 0, v164, s[40:41]
	v_add_f32_e32 v43, v43, v42
	v_add_f32_e32 v44, v149, v43
	v_add_f32_e32 v43, v150, v43
	v_add_f32_e32 v40, v40, v43
	v_add_f32_e32 v38, v38, v40
	v_add_f32_e32 v39, v39, v40
	v_add_f32_e32 v40, v151, v42
	v_cndmask_b32_e64 v42, 0, v163, s[40:41]
	v_add_f32_e32 v42, v42, v40
	v_add_f32_e32 v37, v37, v42
	v_add_f32_e32 v36, v36, v37
	v_add_f32_e32 v34, v34, v36
	v_add_f32_e32 v39, v146, v39
	v_exp_f32_e32 v146, v34
	v_add_f32_e32 v34, v35, v36
	v_add_f32_e32 v34, v142, v34
	v_exp_f32_e32 v142, v34
	v_add_f32_e32 v34, v147, v40
	v_cndmask_b32_e64 v35, 0, v162, s[40:41]
	v_add_f32_e32 v35, v35, v34
	v_add_f32_e32 v36, v141, v35
	v_add_f32_e32 v35, v65, v35
	v_exp_f32_e32 v149, v44
	v_add_f32_e32 v44, v148, v43
	v_add_f32_e32 v43, v145, v42
	v_add_f32_e32 v42, v144, v37
	v_exp_f32_e32 v37, v36
	v_add_f32_e32 v36, v140, v35
	v_add_f32_e32 v35, v64, v35
	v_exp_f32_e32 v40, v36
	v_add_f32_e32 v36, v62, v35
	v_add_f32_e32 v35, v63, v35
	v_add_f32_e32 v35, v138, v35
	v_add_f32_e32 v139, v139, v161
	v_exp_f32_e32 v144, v42
	v_exp_f32_e32 v42, v35
	v_add_f32_e32 v34, v143, v34
	v_cndmask_b32_e64 v35, 0, v161, s[40:41]
	v_add_f32_e32 v35, v35, v34
	v_add_f32_e32 v34, v139, v34
	v_cndmask_b32_e64 v46, 0, v133, s[40:41]
	v_add_f32_e32 v47, v152, v45
	v_add_f32_e32 v46, v46, v34
	v_exp_f32_e32 v152, v47
	v_exp_f32_e32 v145, v43
	v_add_f32_e32 v43, v137, v35
	v_add_f32_e32 v35, v61, v35
	v_add_f32_e32 v47, v132, v46
	v_add_f32_e32 v46, v57, v46
	v_add_f32_e32 v136, v136, v133
	v_exp_f32_e32 v126, v48
	v_exp_f32_e32 v148, v44
	v_add_f32_e32 v44, v135, v35
	v_add_f32_e32 v35, v60, v35
	v_add_f32_e32 v48, v131, v46
	v_add_f32_e32 v46, v56, v46
	v_add_f32_e32 v156, v156, v49
	v_add_f32_e32 v45, v58, v35
	v_add_f32_e32 v35, v59, v35
	v_add_f32_e32 v49, v54, v46
	v_add_f32_e32 v46, v55, v46
	v_add_f32_e32 v54, v136, v34
	v_cndmask_b32_e64 v34, 0, v160, s[40:41]
	v_add_f32_e32 v35, v134, v35
	v_add_f32_e32 v46, v130, v46
	v_add_f32_e32 v34, v34, v54
	v_exp_f32_e32 v43, v43
	v_exp_f32_e32 v44, v44
	v_exp_f32_e32 v45, v45
	v_exp_f32_e32 v35, v35
	v_exp_f32_e32 v47, v47
	v_exp_f32_e32 v48, v48
	v_exp_f32_e32 v49, v49
	v_exp_f32_e32 v46, v46
	v_add_f32_e32 v55, v128, v34
	v_add_f32_e32 v34, v53, v34
	v_add_f32_e32 v53, v127, v34
	v_add_f32_e32 v34, v52, v34
	v_add_f32_e32 v50, v50, v34
	v_add_f32_e32 v34, v51, v34
	v_add_f32_e32 v0, v0, v34
	v_exp_f32_e32 v36, v36
	v_exp_f32_e32 v55, v55
	v_exp_f32_e32 v53, v53
	v_exp_f32_e32 v50, v50
	v_exp_f32_e32 v0, v0
	v_cvt_pk_bf16_f32 v34, v35, v45
	v_cvt_pk_bf16_f32 v35, v44, v43
	v_cvt_pk_bf16_f32 v44, v46, v49
	v_cvt_pk_bf16_f32 v45, v48, v47
	ds_read_b64 v[46:47], v110 offset:8192
	ds_read_b64 v[48:49], v111 offset:8192
	v_cvt_pk_bf16_f32 v36, v42, v36
	v_cvt_pk_bf16_f32 v42, v0, v50
	v_cvt_pk_bf16_f32 v43, v53, v55
	v_cvt_pk_bf16_f32 v37, v40, v37
	v_exp_f32_e32 v38, v38
	s_waitcnt lgkmcnt(0)
	v_mfma_f32_32x32x16_bf16 v[18:33], v[46:49], v[42:45], v[18:33]
	ds_read_b64 v[46:47], v112 offset:8192
	ds_read_b64 v[48:49], v113 offset:8192
	v_exp_f32_e32 v39, v39
	v_exp_f32_e32 v129, v129
	v_exp_f32_e32 v156, v156
	s_waitcnt lgkmcnt(0)
	v_mfma_f32_32x32x16_bf16 v[2:17], v[46:49], v[42:45], v[2:17]
	ds_read_b64 v[42:43], v114 offset:8192
	ds_read_b64 v[44:45], v115 offset:8192
	s_waitcnt lgkmcnt(0)
	v_mfma_f32_32x32x16_bf16 v[18:33], v[42:45], v[34:37], v[18:33]
	ds_read_b64 v[42:43], v116 offset:8192
	ds_read_b64 v[44:45], v117 offset:8192
	ds_read_b64 v[46:47], v118 offset:8192
	ds_read_b64 v[48:49], v119 offset:8192
	s_waitcnt lgkmcnt(2)
	v_mfma_f32_32x32x16_bf16 v[2:17], v[42:45], v[34:37], v[2:17]
	v_cvt_pk_bf16_f32 v42, v142, v146
	v_cvt_pk_bf16_f32 v43, v144, v145
	v_cvt_pk_bf16_f32 v44, v39, v38
	v_cvt_pk_bf16_f32 v45, v148, v149
	v_cvt_pk_bf16_f32 v34, v153, v154
	v_cvt_pk_bf16_f32 v35, v152, v126
	v_cvt_pk_bf16_f32 v36, v157, v159
	s_waitcnt lgkmcnt(0)
	v_mfma_f32_32x32x16_bf16 v[18:33], v[46:49], v[42:45], v[18:33]
	ds_read_b64 v[46:47], v120 offset:8192
	ds_read_b64 v[48:49], v121 offset:8192
	v_cvt_pk_bf16_f32 v37, v156, v129
	v_add_f32_e32 v126, v41, v54
	v_cmp_gt_f32_e32 vcc, s0, v126
	s_waitcnt lgkmcnt(0)
	v_mfma_f32_32x32x16_bf16 v[2:17], v[46:49], v[42:45], v[2:17]
	ds_read_b64 v[42:43], v122 offset:8192
	ds_read_b64 v[44:45], v123 offset:8192
	s_waitcnt lgkmcnt(0)
	v_mfma_f32_32x32x16_bf16 v[18:33], v[42:45], v[34:37], v[18:33]
	ds_read_b64 v[42:43], v124 offset:8192
	ds_read_b64 v[44:45], v125 offset:8192
	s_waitcnt lgkmcnt(0)
	v_mfma_f32_32x32x16_bf16 v[2:17], v[42:45], v[34:37], v[2:17]
	v_cndmask_b32_e64 v34, 0, 1, vcc
	s_branch .LBB0_89
